# P7 epilogue quarter batches, x1 loads without the nt hint
# baseline (speedup 1.0000x reference)
;     __device__ __forceinline__ void operator()(const pg8::f32x4 (&acc)[2][2][4][2], const pg8::Unit& u, int wr, int wc, int fr, int fq) const {
;         const int b = u.pm >> 4;
; #pragma unroll
;         for (int bj = 0; bj < 2; ++bj) { const int c0 = u.pn * 256 + bj * 128 + wc * 32 + 8 * fq; const float* g2p = e.mod + (size_t)b * NMOD + 5 * DM + c0; const f32x4 ga = *(const f32x4*)g2p, gb = *(const f32x4*)(g2p + 4);
; #pragma unroll
;             for (int ai = 0; ai < 2; ++ai)
; #pragma unroll
;                 for (int m = 0; m < 4; ++m) { ACC8(v, ai, bj, m); const size_t off = (size_t)(u.pm * 256 + ai * 128 + wr * 64 + m * 16 + fr) * DM + c0;
;                     f32x4 xa = __builtin_nontemporal_load((const f32x4*)(e.out + off)), xc = __builtin_nontemporal_load((const f32x4*)(e.out + off + 4));
; #pragma unroll
;                     for (int i = 0; i < 4; ++i) { xa[i] += ga[i] * v[i]; xc[i] += gb[i] * v[4 + i]; }
;                     float* dst = e.dump ? e.dump + (off & (size_t)0x7ffff8) : e.out + off;
;                     __builtin_nontemporal_store(xa, (f32x4*)dst); __builtin_nontemporal_store(xc, (f32x4*)(dst + 4)); }
.LBB9_856:
	s_ashr_i32 s14, s37, 4
	v_lshl_add_u32 v166, s37, 8, v170
	s_mul_hi_i32 s15, s14, 0x6000
	s_mulk_i32 s14, 0x6000
	v_ashrrev_i32_e32 v167, 31, v166
	s_add_u32 s14, s90, s14
	v_lshlrev_b64 v[152:153], 12, v[166:167]
	v_or_b32_e32 v154, 16, v166
	v_or_b32_e32 v156, 32, v166
	v_or_b32_e32 v158, 48, v166
	v_add_u32_e32 v160, 0x80, v166
	v_add_u32_e32 v162, 0x90, v166
	v_add_u32_e32 v164, 0xa0, v166
	v_add_u32_e32 v166, 0xb0, v166
	v_lshl_or_b32 v168, s38, 8, v172
	s_addc_u32 s15, s91, s15
	v_ashrrev_i32_e32 v155, 31, v154
	v_ashrrev_i32_e32 v157, 31, v156
	v_ashrrev_i32_e32 v159, 31, v158
	v_ashrrev_i32_e32 v161, 31, v160
	v_ashrrev_i32_e32 v163, 31, v162
	v_ashrrev_i32_e32 v165, 31, v164
	v_ashrrev_i32_e32 v167, 31, v166
	s_add_u32 s14, s14, 0x1f45000
	v_ashrrev_i32_e32 v169, 31, v168
	v_lshlrev_b64 v[154:155], 12, v[154:155]
	v_lshlrev_b64 v[156:157], 12, v[156:157]
	v_lshlrev_b64 v[158:159], 12, v[158:159]
	v_lshlrev_b64 v[160:161], 12, v[160:161]
	v_lshlrev_b64 v[162:163], 12, v[162:163]
	v_lshlrev_b64 v[164:165], 12, v[164:165]
	v_lshlrev_b64 v[166:167], 12, v[166:167]
	s_addc_u32 s15, s15, 0
	v_lshlrev_b64 v[232:233], 2, v[168:169]
	v_lshl_add_u64 v[152:153], s[88:89], 0, v[152:153]
	v_lshl_add_u64 v[154:155], s[88:89], 0, v[154:155]
	v_lshl_add_u64 v[156:157], s[88:89], 0, v[156:157]
	v_lshl_add_u64 v[158:159], s[88:89], 0, v[158:159]
	v_lshl_add_u64 v[160:161], s[88:89], 0, v[160:161]
	v_lshl_add_u64 v[162:163], s[88:89], 0, v[162:163]
	v_lshl_add_u64 v[164:165], s[88:89], 0, v[164:165]
	v_lshl_add_u64 v[166:167], s[88:89], 0, v[166:167]
	v_lshl_add_u64 v[132:133], s[14:15], 0, v[232:233]
	v_lshl_add_u64 v[152:153], v[152:153], 0, v[232:233]
	v_lshl_add_u64 v[154:155], v[154:155], 0, v[232:233]
	v_lshl_add_u64 v[156:157], v[156:157], 0, v[232:233]
	v_lshl_add_u64 v[158:159], v[158:159], 0, v[232:233]
	v_lshl_add_u64 v[160:161], v[160:161], 0, v[232:233]
	v_lshl_add_u64 v[162:163], v[162:163], 0, v[232:233]
	v_lshl_add_u64 v[164:165], v[164:165], 0, v[232:233]
	v_lshl_add_u64 v[166:167], v[166:167], 0, v[232:233]
	global_load_dwordx4 v[128:131], v[132:133], off offset:16
	s_nop 0
	global_load_dwordx4 v[132:135], v[132:133], off
	v_or_b32_e32 v248, 0x80, v168
	v_ashrrev_i32_e32 v249, 31, v248
	v_lshl_add_u64 v[248:249], v[248:249], 2, s[14:15]
	global_load_dwordx4 v[240:243], v[248:249], off
	global_load_dwordx4 v[244:247], v[248:249], off offset:16
	global_load_dwordx4 v[176:179], v[152:153], off
	global_load_dwordx4 v[180:183], v[152:153], off offset:16
	global_load_dwordx4 v[184:187], v[154:155], off
	global_load_dwordx4 v[188:191], v[154:155], off offset:16
	global_load_dwordx4 v[192:195], v[156:157], off
	global_load_dwordx4 v[196:199], v[156:157], off offset:16
	global_load_dwordx4 v[200:203], v[158:159], off
	global_load_dwordx4 v[204:207], v[158:159], off offset:16
	global_load_dwordx4 v[208:211], v[160:161], off
	global_load_dwordx4 v[212:215], v[160:161], off offset:16
	global_load_dwordx4 v[216:219], v[162:163], off
	global_load_dwordx4 v[220:223], v[162:163], off offset:16
	global_load_dwordx4 v[224:227], v[164:165], off
	global_load_dwordx4 v[228:231], v[164:165], off offset:16
	global_load_dwordx4 v[232:235], v[166:167], off
	global_load_dwordx4 v[236:239], v[166:167], off offset:16
	s_and_b64 vcc, exec, s[0:1]
	s_mov_b64 s[0:1], -1
	s_waitcnt vmcnt(8)
	v_pk_fma_f32 v[124:125], v[124:125], v[132:133], v[176:177]
	v_pk_fma_f32 v[126:127], v[126:127], v[134:135], v[178:179]
	v_pk_fma_f32 v[120:121], v[120:121], v[128:129], v[180:181]
	v_pk_fma_f32 v[122:123], v[122:123], v[130:131], v[182:183]
	v_pk_fma_f32 v[116:117], v[116:117], v[132:133], v[184:185]
	v_pk_fma_f32 v[118:119], v[118:119], v[134:135], v[186:187]
	v_pk_fma_f32 v[112:113], v[112:113], v[128:129], v[188:189]
	v_pk_fma_f32 v[114:115], v[114:115], v[130:131], v[190:191]
	v_pk_fma_f32 v[108:109], v[108:109], v[132:133], v[192:193]
	v_pk_fma_f32 v[110:111], v[110:111], v[134:135], v[194:195]
	v_pk_fma_f32 v[104:105], v[104:105], v[128:129], v[196:197]
	v_pk_fma_f32 v[106:107], v[106:107], v[130:131], v[198:199]
	v_pk_fma_f32 v[100:101], v[100:101], v[132:133], v[200:201]
	v_pk_fma_f32 v[102:103], v[102:103], v[134:135], v[202:203]
	v_pk_fma_f32 v[96:97], v[96:97], v[128:129], v[204:205]
	v_pk_fma_f32 v[98:99], v[98:99], v[130:131], v[206:207]
	global_load_dwordx4 v[176:179], v[152:153], off offset:512
	global_load_dwordx4 v[180:183], v[152:153], off offset:528
	global_load_dwordx4 v[184:187], v[154:155], off offset:512
	global_load_dwordx4 v[188:191], v[154:155], off offset:528
	global_load_dwordx4 v[192:195], v[156:157], off offset:512
	global_load_dwordx4 v[196:199], v[156:157], off offset:528
	global_load_dwordx4 v[200:203], v[158:159], off offset:512
	global_load_dwordx4 v[204:207], v[158:159], off offset:528
	global_store_dwordx4 v[152:153], v[124:127], off
	global_store_dwordx4 v[152:153], v[120:123], off offset:16
	global_store_dwordx4 v[154:155], v[116:119], off
	global_store_dwordx4 v[154:155], v[112:115], off offset:16
	global_store_dwordx4 v[156:157], v[108:111], off
	global_store_dwordx4 v[156:157], v[104:107], off offset:16
	global_store_dwordx4 v[158:159], v[100:103], off
	global_store_dwordx4 v[158:159], v[96:99], off offset:16
	s_waitcnt vmcnt(16)
;     __device__ __forceinline__ void operator()(const pg8::f32x4 (&acc)[2][2][4][2], const pg8::Unit& u, int wr, int wc, int fr, int fq) const {
;         const int b = u.pm >> 4;
; #pragma unroll
;         for (int bj = 0; bj < 2; ++bj) { const int c0 = u.pn * 256 + bj * 128 + wc * 32 + 8 * fq; const float* g2p = e.mod + (size_t)b * NMOD + 5 * DM + c0; const f32x4 ga = *(const f32x4*)g2p, gb = *(const f32x4*)(g2p + 4);
; #pragma unroll
;             for (int ai = 0; ai < 2; ++ai)
; #pragma unroll
;                 for (int m = 0; m < 4; ++m) { ACC8(v, ai, bj, m); const size_t off = (size_t)(u.pm * 256 + ai * 128 + wr * 64 + m * 16 + fr) * DM + c0;
;                     f32x4 xa = __builtin_nontemporal_load((const f32x4*)(e.out + off)), xc = __builtin_nontemporal_load((const f32x4*)(e.out + off + 4));
; #pragma unroll
;                     for (int i = 0; i < 4; ++i) { xa[i] += ga[i] * v[i]; xc[i] += gb[i] * v[4 + i]; }
;                     float* dst = e.dump ? e.dump + (off & (size_t)0x7ffff8) : e.out + off;
;                     __builtin_nontemporal_store(xa, (f32x4*)dst); __builtin_nontemporal_store(xc, (f32x4*)(dst + 4)); }
	v_pk_fma_f32 v[92:93], v[92:93], v[132:133], v[208:209]
	v_pk_fma_f32 v[94:95], v[94:95], v[134:135], v[210:211]
	v_pk_fma_f32 v[88:89], v[88:89], v[128:129], v[212:213]
	v_pk_fma_f32 v[90:91], v[90:91], v[130:131], v[214:215]
	v_pk_fma_f32 v[84:85], v[84:85], v[132:133], v[216:217]
	v_pk_fma_f32 v[86:87], v[86:87], v[134:135], v[218:219]
	v_pk_fma_f32 v[80:81], v[80:81], v[128:129], v[220:221]
	v_pk_fma_f32 v[82:83], v[82:83], v[130:131], v[222:223]
	v_pk_fma_f32 v[76:77], v[76:77], v[132:133], v[224:225]
	v_pk_fma_f32 v[78:79], v[78:79], v[134:135], v[226:227]
	v_pk_fma_f32 v[72:73], v[72:73], v[128:129], v[228:229]
	v_pk_fma_f32 v[74:75], v[74:75], v[130:131], v[230:231]
	v_pk_fma_f32 v[68:69], v[68:69], v[132:133], v[232:233]
	v_pk_fma_f32 v[70:71], v[70:71], v[134:135], v[234:235]
	v_pk_fma_f32 v[64:65], v[64:65], v[128:129], v[236:237]
	v_pk_fma_f32 v[66:67], v[66:67], v[130:131], v[238:239]
	global_load_dwordx4 v[208:211], v[160:161], off offset:512
	global_load_dwordx4 v[212:215], v[160:161], off offset:528
	global_load_dwordx4 v[216:219], v[162:163], off offset:512
	global_load_dwordx4 v[220:223], v[162:163], off offset:528
	global_load_dwordx4 v[224:227], v[164:165], off offset:512
	global_load_dwordx4 v[228:231], v[164:165], off offset:528
	global_load_dwordx4 v[232:235], v[166:167], off offset:512
	global_load_dwordx4 v[236:239], v[166:167], off offset:528
	global_store_dwordx4 v[160:161], v[92:95], off
	global_store_dwordx4 v[160:161], v[88:91], off offset:16
	global_store_dwordx4 v[162:163], v[84:87], off
	global_store_dwordx4 v[162:163], v[80:83], off offset:16
	global_store_dwordx4 v[164:165], v[76:79], off
	global_store_dwordx4 v[164:165], v[72:75], off offset:16
	global_store_dwordx4 v[166:167], v[68:71], off
	global_store_dwordx4 v[166:167], v[64:67], off offset:16
	s_waitcnt vmcnt(24)
	v_pk_fma_f32 v[60:61], v[60:61], v[240:241], v[176:177]
	v_pk_fma_f32 v[62:63], v[62:63], v[242:243], v[178:179]
	v_pk_fma_f32 v[56:57], v[56:57], v[244:245], v[180:181]
	v_pk_fma_f32 v[58:59], v[58:59], v[246:247], v[182:183]
	v_pk_fma_f32 v[52:53], v[52:53], v[240:241], v[184:185]
	v_pk_fma_f32 v[54:55], v[54:55], v[242:243], v[186:187]
	v_pk_fma_f32 v[48:49], v[48:49], v[244:245], v[188:189]
	v_pk_fma_f32 v[50:51], v[50:51], v[246:247], v[190:191]
	v_pk_fma_f32 v[44:45], v[44:45], v[240:241], v[192:193]
	v_pk_fma_f32 v[46:47], v[46:47], v[242:243], v[194:195]
	v_pk_fma_f32 v[40:41], v[40:41], v[244:245], v[196:197]
	v_pk_fma_f32 v[42:43], v[42:43], v[246:247], v[198:199]
	v_pk_fma_f32 v[36:37], v[36:37], v[240:241], v[200:201]
	v_pk_fma_f32 v[38:39], v[38:39], v[242:243], v[202:203]
	v_pk_fma_f32 v[32:33], v[32:33], v[244:245], v[204:205]
	v_pk_fma_f32 v[34:35], v[34:35], v[246:247], v[206:207]
	global_store_dwordx4 v[152:153], v[60:63], off offset:512
	global_store_dwordx4 v[152:153], v[56:59], off offset:528
	global_store_dwordx4 v[154:155], v[52:55], off offset:512
	global_store_dwordx4 v[154:155], v[48:51], off offset:528
	global_store_dwordx4 v[156:157], v[44:47], off offset:512
	global_store_dwordx4 v[156:157], v[40:43], off offset:528
	global_store_dwordx4 v[158:159], v[36:39], off offset:512
	global_store_dwordx4 v[158:159], v[32:35], off offset:528
	s_waitcnt vmcnt(16)
	v_pk_fma_f32 v[28:29], v[28:29], v[240:241], v[208:209]
	v_pk_fma_f32 v[30:31], v[30:31], v[242:243], v[210:211]
	v_pk_fma_f32 v[24:25], v[24:25], v[244:245], v[212:213]
	v_pk_fma_f32 v[26:27], v[26:27], v[246:247], v[214:215]
	v_pk_fma_f32 v[20:21], v[20:21], v[240:241], v[216:217]
	v_pk_fma_f32 v[22:23], v[22:23], v[242:243], v[218:219]
	v_pk_fma_f32 v[16:17], v[16:17], v[244:245], v[220:221]
	v_pk_fma_f32 v[18:19], v[18:19], v[246:247], v[222:223]
	v_pk_fma_f32 v[12:13], v[12:13], v[240:241], v[224:225]
	v_pk_fma_f32 v[14:15], v[14:15], v[242:243], v[226:227]
	v_pk_fma_f32 v[8:9], v[8:9], v[244:245], v[228:229]
	v_pk_fma_f32 v[10:11], v[10:11], v[246:247], v[230:231]
	v_pk_fma_f32 v[4:5], v[4:5], v[240:241], v[232:233]
	v_pk_fma_f32 v[6:7], v[6:7], v[242:243], v[234:235]
	v_pk_fma_f32 v[0:1], v[0:1], v[244:245], v[236:237]
	v_pk_fma_f32 v[2:3], v[2:3], v[246:247], v[238:239]
	global_store_dwordx4 v[160:161], v[28:31], off offset:512
	global_store_dwordx4 v[160:161], v[24:27], off offset:528
	global_store_dwordx4 v[162:163], v[20:23], off offset:512
	global_store_dwordx4 v[162:163], v[16:19], off offset:528
	global_store_dwordx4 v[164:165], v[12:15], off offset:512
	global_store_dwordx4 v[164:165], v[8:11], off offset:528
	global_store_dwordx4 v[166:167], v[4:7], off offset:512
	global_store_dwordx4 v[166:167], v[0:3], off offset:528
	s_cbranch_vccnz .LBB9_841
	s_andn2_b64 vcc, exec, s[6:7]
	s_cbranch_vccnz .LBB9_840
	s_barrier
	s_branch .LBB9_840
